# attention queue atomic no longer stalls wave 0 at unit top; s5_s3 group prefetch of u rows; first-barrier census loads batched
# speedup vs baseline: 1.0151x; 1.0028x over previous
.LBB0_976:
	v_readlane_b32 s6, v252, 45
	v_readlane_b32 s7, v252, 46
	v_readlane_b32 s8, v254, 37
	s_mov_b64 s[38:39], -1
	s_nop 2
	global_load_dword v0, v1, s[6:7] sc1
	v_readlane_b32 s6, v252, 47
	v_readlane_b32 s7, v252, 48
	s_waitcnt lgkmcnt(0)
	s_nop 3
	global_load_dword v2, v1, s[6:7] sc1
	v_readlane_b32 s6, v252, 49
	v_readlane_b32 s7, v252, 50
	s_nop 1
	s_nop 2
	global_load_dword v3, v1, s[6:7] sc1
	v_readlane_b32 s6, v252, 51
	v_readlane_b32 s7, v252, 52
	s_nop 1
	s_nop 2
	global_load_dword v4, v1, s[6:7] sc1
	v_readlane_b32 s6, v252, 53
	v_readlane_b32 s7, v252, 54
	s_nop 1
	s_nop 2
	global_load_dword v5, v1, s[6:7] sc1
	v_readlane_b32 s6, v252, 55
	v_readlane_b32 s7, v252, 56
	s_nop 1
	s_nop 2
	global_load_dword v6, v1, s[6:7] sc1
	v_readlane_b32 s6, v252, 57
	v_readlane_b32 s7, v252, 58
	s_nop 1
	s_nop 2
	global_load_dword v7, v1, s[6:7] sc1
	v_readlane_b32 s6, v252, 59
	v_readlane_b32 s7, v252, 60
	s_nop 1
	s_nop 2
	global_load_dword v8, v1, s[6:7] sc1
	v_readlane_b32 s6, v252, 61
	v_readlane_b32 s7, v252, 62
	s_nop 1
	s_nop 2
	global_load_dword v9, v1, s[6:7] sc1
	v_readlane_b32 s6, v252, 63
	v_readlane_b32 s7, v253, 0
	s_nop 1
	s_nop 2
	global_load_dword v10, v1, s[6:7] sc1
	v_readlane_b32 s6, v253, 1
	v_readlane_b32 s7, v253, 2
	s_nop 1
	s_nop 2
	global_load_dword v11, v1, s[6:7] sc1
	v_readlane_b32 s6, v253, 3
	v_readlane_b32 s7, v253, 4
	s_nop 1
	s_nop 2
	global_load_dword v12, v1, s[6:7] sc1
	v_readlane_b32 s6, v253, 5
	v_readlane_b32 s7, v253, 6
	s_nop 1
	s_nop 2
	global_load_dword v13, v1, s[6:7] sc1
	v_readlane_b32 s6, v253, 7
	v_readlane_b32 s7, v253, 8
	s_nop 1
	s_nop 2
	global_load_dword v14, v1, s[6:7] sc1
	v_readlane_b32 s6, v253, 9
	v_readlane_b32 s7, v253, 10
	s_nop 1
	s_nop 2
	global_load_dword v15, v1, s[6:7] sc1
	v_readlane_b32 s6, v253, 11
	v_readlane_b32 s7, v253, 12
	s_nop 1
	s_nop 2
	global_load_dword v16, v1, s[6:7] sc1
	s_mov_b64 s[6:7], -1
	s_waitcnt vmcnt(0)
	v_add_u32_e32 v17, v2, v0
	v_add_u32_e32 v17, v17, v3
	v_add_u32_e32 v17, v17, v4
	v_add_u32_e32 v17, v17, v5
	v_add_u32_e32 v17, v17, v6
	v_add_u32_e32 v17, v17, v7
	v_add_u32_e32 v17, v17, v8
	v_add_u32_e32 v17, v17, v9
	v_add_u32_e32 v17, v17, v10
	v_add_u32_e32 v17, v17, v11
	v_add_u32_e32 v17, v17, v12
	v_add_u32_e32 v17, v17, v13
	v_add_u32_e32 v17, v17, v14
	v_add_u32_e32 v17, v17, v15
	v_add_u32_e32 v17, v17, v16
	v_cmp_eq_u32_e32 vcc, s8, v17
	s_cbranch_vccnz .LBB0_975
	s_and_b32 s6, s1, 0xff
	s_cmp_eq_u32 s6, 0
	s_mov_b64 s[6:7], -1
	s_mov_b64 s[40:41], -1
	s_sleep 1
	s_cbranch_scc1 .LBB0_980
	s_and_b64 vcc, exec, s[40:41]
	s_cbranch_vccz .LBB0_975

.LBB0_1120:
	s_or_b64 exec, exec, s[46:47]
	s_lshl_b32 s11, s11, 2
	s_add_i32 s11, s11, 0
	v_readlane_b32 s26, v252, 37
	s_add_i32 s11, s11, 0x23000
	v_readlane_b32 s27, v252, 38
	v_mov_b32_e32 v2, s11
	s_waitcnt lgkmcnt(0)
	v_mov_b32_e32 v3, s27
	s_and_saveexec_b64 s[100:101], s[40:41]
	s_cbranch_execz .Lattnq_skip
	s_waitcnt vmcnt(0)
	flat_store_dword v[2:3], v240 sc0 sc1
	s_waitcnt vmcnt(0) lgkmcnt(0)
.Lattnq_skip:
	s_or_b64 exec, exec, s[100:101]
	s_barrier
	flat_load_dword v52, v[2:3] sc0 sc1
	s_waitcnt vmcnt(0)
	s_movk_i32 s11, 0x7ff
	v_cmp_lt_i32_e32 vcc, s11, v199
	s_or_b64 s[56:57], vcc, s[56:57]
	s_mov_b32 s11, s10
	v_mov_b32_e32 v99, v199
	s_andn2_b64 exec, exec, s[56:57]
	s_cbranch_execz .LBB0_1141
.LBB0_1121:
	s_waitcnt lgkmcnt(0)
	v_mov_b32_e32 v199, v52
	s_and_saveexec_b64 s[44:45], s[40:41]
	s_cbranch_execz .LBB0_1123
	v_mov_b64_e32 v[2:3], s[4:5]
	global_atomic_add v240, v[2:3], v225, off sc0
	s_lshl_b32 s10, s11, 2
	s_add_i32 s10, s10, 0
	v_readlane_b32 s26, v252, 37
	s_add_i32 s10, s10, 0x23000
	v_readlane_b32 s27, v252, 38
	v_mov_b32_e32 v2, s10
	s_nop 0
	v_mov_b32_e32 v3, s27

.LBB0_1197:
	s_add_i32 s6, s12, s44
	v_mov_b64_e32 v[202:203], s[0:1]
	v_or_b32_e32 v206, 16, v92
	s_lshl_b32 s100, s6, 6
	s_mov_b32 s101, 0
	v_mad_i64_i32 v[204:205], vcc, v92, s20, v[202:203]
	v_mad_i64_i32 v[206:207], vcc, v206, s20, v[202:203]
	v_lshl_add_u64 v[204:205], v[204:205], 0, s[100:101]
	v_lshl_add_u64 v[206:207], v[206:207], 0, s[100:101]
	v_lshl_add_u64 v[204:205], v[204:205], 0, s[94:95]
	v_lshl_add_u64 v[206:207], v[206:207], 0, s[94:95]
	v_lshl_add_u64 v[208:209], v[204:205], 0, v[0:1]
	v_lshl_add_u64 v[210:211], v[206:207], 0, v[0:1]
	global_load_dwordx4 v[140:143], v[208:209], off
	global_load_dwordx4 v[152:155], v[210:211], off
	v_mov_b32_e32 v208, v82
	v_mov_b32_e32 v209, 0
	s_mov_b64 s[100:101], exec
	s_and_b64 exec, exec, s[42:43]
	v_lshl_add_u64 v[210:211], v[204:205], 0, v[208:209]
	global_load_dwordx4 v[132:135], v[210:211], off
	global_load_dwordx4 v[136:139], v[210:211], off offset:16
	v_lshl_add_u64 v[210:211], v[206:207], 0, v[208:209]
	global_load_dwordx4 v[144:147], v[210:211], off
	global_load_dwordx4 v[148:151], v[210:211], off offset:16
	s_mov_b64 exec, s[100:101]
	s_ashr_i32 s7, s6, 31
	s_lshl_b64 s[4:5], s[6:7], 16
	v_lshl_add_u64 v[2:3], v[94:95], 0, s[4:5]
	s_add_i32 s4, s6, s60
	s_ashr_i32 s5, s4, 31
	s_lshl_b64 s[34:35], s[4:5], 10
	flat_load_dwordx2 v[96:97], v[2:3]
	v_lshl_add_u64 v[2:3], v[66:67], 0, s[34:35]
	flat_load_dwordx4 v[126:129], v[2:3]
	s_lshl_b64 s[34:35], s[4:5], 12
	v_lshl_add_u64 v[4:5], v[68:69], 0, s[34:35]
	flat_load_dwordx4 v[8:11], v[4:5]
	flat_load_dwordx4 v[12:15], v[4:5] offset:512
	flat_load_dwordx4 v[16:19], v[4:5] offset:1024
	flat_load_dwordx4 v[20:23], v[4:5] offset:1536
	flat_load_dwordx4 v[24:27], v[4:5] offset:2048
	flat_load_dwordx4 v[28:31], v[4:5] offset:2560
	flat_load_dwordx4 v[32:35], v[4:5] offset:3072
	flat_load_dwordx4 v[36:39], v[4:5] offset:3584
	v_lshl_or_b32 v4, v64, 8, s34
	v_mov_b32_e32 v5, s35
	v_lshl_add_u64 v[56:57], v[70:71], 0, v[4:5]
	v_lshl_add_u64 v[58:59], v[72:73], 0, v[4:5]
	global_load_dwordx4 v[48:51], v[56:57], off
	global_load_dwordx4 v[40:43], v[56:57], off offset:16
	global_load_dwordx4 v[4:7], v[58:59], off offset:16
	global_load_dwordx4 v[44:47], v[58:59], off
	s_lshl_b64 s[4:5], s[4:5], 6
	v_lshl_add_u32 v81, s6, 5, v65
	s_mov_b64 s[38:39], -1
	s_mov_b32 s18, 0
	s_waitcnt vmcnt(0) lgkmcnt(0)
	v_mov_b32_e32 v2, v126
	v_mov_b32_e32 v3, v127
	v_cndmask_b32_e64 v11, v11, 0, s[40:41]
	v_cndmask_b32_e64 v10, v10, 0, s[40:41]
	v_cndmask_b32_e64 v9, v9, 0, s[40:41]
	v_cndmask_b32_e64 v8, v8, 0, s[40:41]
	v_cndmask_b32_e64 v15, v15, 0, s[40:41]
	v_cndmask_b32_e64 v14, v14, 0, s[40:41]
	v_cndmask_b32_e64 v13, v13, 0, s[40:41]
	v_cndmask_b32_e64 v12, v12, 0, s[40:41]
	v_cndmask_b32_e64 v19, v19, 0, s[40:41]
	v_bfe_u32 v122, v51, 16, 1
	v_bfe_u32 v118, v43, 16, 1
	v_xor_b32_e32 v83, 0x80000000, v4
	v_xor_b32_e32 v60, 0x80000000, v44
	v_xor_b32_e32 v61, 0x80000000, v45
	v_xor_b32_e32 v62, 0x80000000, v46
	v_xor_b32_e32 v63, 0x80000000, v47
	v_xor_b32_e32 v93, 0x80000000, v5
	v_xor_b32_e32 v98, 0x80000000, v6
	v_xor_b32_e32 v99, 0x80000000, v7
	global_load_dwordx4 v[52:55], v[56:57], off offset:128
	global_load_dwordx4 v[44:47], v[56:57], off offset:144
	global_load_dwordx4 v[4:7], v[58:59], off offset:144
	s_nop 0
	global_load_dwordx4 v[56:59], v[58:59], off offset:128
	v_bfe_u32 v119, v42, 16, 1
	v_bfe_u32 v120, v41, 16, 1
	v_bfe_u32 v121, v40, 16, 1
	v_bfe_u32 v123, v50, 16, 1
	v_bfe_u32 v124, v49, 16, 1
	v_bfe_u32 v125, v48, 16, 1
	v_add3_u32 v48, v48, v125, s23
	v_add3_u32 v49, v49, v124, s23
	v_add3_u32 v50, v50, v123, s23
	v_add3_u32 v51, v51, v122, s23
	v_add3_u32 v40, v40, v121, s23
	v_add3_u32 v41, v41, v120, s23
	v_add3_u32 v42, v42, v119, s23
	v_add3_u32 v43, v43, v118, s23
	v_perm_b32 v43, v43, v42, s22
	v_perm_b32 v42, v41, v40, s22
	v_perm_b32 v41, v51, v50, s22
	v_perm_b32 v40, v49, v48, s22
	v_cndmask_b32_e64 v18, v18, 0, s[40:41]
	v_cndmask_b32_e64 v17, v17, 0, s[40:41]
	v_cndmask_b32_e64 v16, v16, 0, s[40:41]
	v_cndmask_b32_e64 v23, v23, 0, s[40:41]
	v_cndmask_b32_e64 v22, v22, 0, s[40:41]
	v_cndmask_b32_e64 v21, v21, 0, s[40:41]
	v_cndmask_b32_e64 v20, v20, 0, s[40:41]
	v_cndmask_b32_e64 v27, v27, 0, s[40:41]
	v_cndmask_b32_e64 v26, v26, 0, s[40:41]
	v_cndmask_b32_e64 v25, v25, 0, s[40:41]
	v_cndmask_b32_e64 v24, v24, 0, s[40:41]
	v_cndmask_b32_e64 v31, v31, 0, s[40:41]
	v_cndmask_b32_e64 v30, v30, 0, s[40:41]
	v_cndmask_b32_e64 v29, v29, 0, s[40:41]
	v_cndmask_b32_e64 v28, v28, 0, s[40:41]
	v_cndmask_b32_e64 v35, v35, 0, s[40:41]
	v_cndmask_b32_e64 v34, v34, 0, s[40:41]
	v_cndmask_b32_e64 v33, v33, 0, s[40:41]
	v_cndmask_b32_e64 v32, v32, 0, s[40:41]
	v_cndmask_b32_e64 v39, v39, 0, s[40:41]
	v_cndmask_b32_e64 v38, v38, 0, s[40:41]
	v_cndmask_b32_e64 v37, v37, 0, s[40:41]
	v_cndmask_b32_e64 v36, v36, 0, s[40:41]
	s_waitcnt vmcnt(3)
	v_bfe_u32 v118, v55, 16, 1
	s_waitcnt vmcnt(2)
	v_bfe_u32 v48, v47, 16, 1
	s_waitcnt vmcnt(1)
	v_xor_b32_e32 v114, 0x80000000, v4
	v_xor_b32_e32 v115, 0x80000000, v5
	v_lshl_add_u64 v[4:5], v[74:75], 0, s[4:5]
	v_xor_b32_e32 v116, 0x80000000, v6
	v_xor_b32_e32 v117, 0x80000000, v7
	global_load_dwordx4 v[4:7], v[4:5], off
	v_bfe_u32 v49, v46, 16, 1
	v_bfe_u32 v50, v45, 16, 1
	v_bfe_u32 v51, v44, 16, 1
	v_bfe_u32 v119, v54, 16, 1
	v_bfe_u32 v120, v53, 16, 1
	v_bfe_u32 v121, v52, 16, 1
	v_add3_u32 v52, v52, v121, s23
	v_add3_u32 v53, v53, v120, s23
	v_add3_u32 v54, v54, v119, s23
	v_add3_u32 v55, v55, v118, s23
	v_add3_u32 v44, v44, v51, s23
	v_add3_u32 v45, v45, v50, s23
	v_add3_u32 v46, v46, v49, s23
	v_add3_u32 v47, v47, v48, s23
	v_perm_b32 v47, v47, v46, s22
	v_perm_b32 v46, v45, v44, s22
	v_perm_b32 v45, v55, v54, s22
	v_perm_b32 v44, v53, v52, s22
	v_bfe_u32 v48, v99, 16, 1
	v_bfe_u32 v49, v98, 16, 1
	v_bfe_u32 v50, v93, 16, 1
	v_bfe_u32 v51, v83, 16, 1
	v_bfe_u32 v52, v63, 16, 1
	v_bfe_u32 v53, v62, 16, 1
	v_bfe_u32 v54, v61, 16, 1
	v_bfe_u32 v55, v60, 16, 1
	s_waitcnt vmcnt(1)
	v_xor_b32_e32 v56, 0x80000000, v56
	v_xor_b32_e32 v57, 0x80000000, v57
	v_xor_b32_e32 v58, 0x80000000, v58
	v_xor_b32_e32 v59, 0x80000000, v59
	v_add3_u32 v55, v60, v55, s23
	v_add3_u32 v54, v61, v54, s23
	v_add3_u32 v53, v62, v53, s23
	v_add3_u32 v52, v63, v52, s23
	v_add3_u32 v60, v83, v51, s23
	v_add3_u32 v50, v93, v50, s23
	v_add3_u32 v49, v98, v49, s23
	v_add3_u32 v48, v99, v48, s23
	v_perm_b32 v51, v48, v49, s22
	v_perm_b32 v50, v50, v60, s22
	v_perm_b32 v49, v52, v53, s22
	v_perm_b32 v48, v54, v55, s22
	v_bfe_u32 v52, v117, 16, 1
	v_bfe_u32 v53, v116, 16, 1
	v_bfe_u32 v54, v115, 16, 1
	v_bfe_u32 v55, v114, 16, 1
	v_bfe_u32 v60, v59, 16, 1
	v_bfe_u32 v61, v58, 16, 1
	v_bfe_u32 v62, v57, 16, 1
	v_bfe_u32 v63, v56, 16, 1
	s_lshl_b32 s4, s6, 4
	v_add3_u32 v56, v56, v63, s23
	v_add3_u32 v57, v57, v62, s23
	v_add3_u32 v58, v58, v61, s23
	v_add3_u32 v59, v59, v60, s23
	v_add3_u32 v60, v114, v55, s23
	v_add3_u32 v54, v115, v54, s23
	v_add3_u32 v53, v116, v53, s23
	v_add3_u32 v52, v117, v52, s23
	s_ashr_i32 s5, s4, 31
	v_perm_b32 v55, v52, v53, s22
	v_perm_b32 v54, v54, v60, s22
	v_perm_b32 v53, v59, v58, s22
	v_perm_b32 v52, v57, v56, s22
	v_pk_mov_b32 v[98:99], v[2:3], v[2:3] op_sel:[1,0]
	s_branch .LBB0_1199
.LBB0_1198:
	s_or_b64 exec, exec, s[6:7]
	v_mfma_f32_16x16x32_bf16 v[114:117], v[60:63], v[8:11], 0
	v_lshl_add_u64 v[56:57], v[56:57], 0, v[0:1]
	v_add_u32_e32 v83, 0x400, v101
	v_mov_b32_e32 v56, v140
	v_mov_b32_e32 v57, v141
	v_mov_b32_e32 v58, v142
	v_mov_b32_e32 v59, v143
	v_mfma_f32_16x16x32_bf16 v[118:121], v[60:63], v[12:15], 0
	s_nop 7
	ds_write2_b32 v101, v114, v118 offset1:16
	ds_write2_b32 v101, v115, v119 offset0:132 offset1:148
	ds_write2_b32 v83, v116, v120 offset0:8 offset1:24
	ds_write2_b32 v83, v117, v121 offset0:140 offset1:156
	v_mfma_f32_16x16x32_bf16 v[114:117], v[60:63], v[16:19], 0
	s_nop 7
	ds_write_b32 v101, v114 offset:128
	ds_write_b32 v101, v115 offset:656
	ds_write_b32 v101, v116 offset:1184
	ds_write_b32 v101, v117 offset:1712
	v_mfma_f32_16x16x32_bf16 v[114:117], v[60:63], v[20:23], 0
	v_add_u32_e32 v93, 0x400, v103
	s_xor_b64 s[6:7], s[38:39], -1
	s_mov_b64 s[38:39], 0
	v_mfma_f32_16x16x32_bf16 v[118:121], v[60:63], v[28:31], 0
	s_nop 3
	ds_write2_b32 v103, v114, v115 offset1:132
	ds_write2_b32 v93, v116, v117 offset0:8 offset1:140
	v_mfma_f32_16x16x32_bf16 v[114:117], v[60:63], v[24:27], 0
	s_nop 7
	ds_write2_b32 v101, v114, v118 offset0:64 offset1:80
	ds_write2_b32 v101, v115, v119 offset0:196 offset1:212
	ds_write2_b32 v83, v116, v120 offset0:72 offset1:88
	ds_write2_b32 v83, v117, v121 offset0:204 offset1:220
	v_mfma_f32_16x16x32_bf16 v[114:117], v[60:63], v[32:35], 0
	s_nop 7
	ds_write_b32 v101, v114 offset:384
	ds_write_b32 v101, v115 offset:912
	ds_write_b32 v101, v116 offset:1440
	ds_write_b32 v101, v117 offset:1968
	v_mfma_f32_16x16x32_bf16 v[60:63], v[60:63], v[36:39], 0
	s_nop 7
	ds_write2_b32 v104, v60, v61 offset1:132
	v_add_u32_e32 v60, 0x400, v104
	ds_write2_b32 v60, v62, v63 offset0:8 offset1:140
	s_waitcnt lgkmcnt(0)
	ds_read2st64_b32 v[60:61], v105 offset1:1
	v_mul_f32_e32 v62, v3, v97
	v_fma_f32 v62, v2, v96, -v62
	s_waitcnt lgkmcnt(0)
	v_add_f32_e32 v62, v62, v60
	v_mul_f32_e32 v60, v2, v97
	v_fmac_f32_e32 v60, v3, v96
	v_add_f32_e32 v63, v60, v61
	ds_read2_b32 v[60:61], v105 offset0:132 offset1:196
	v_mul_f32_e32 v83, v3, v63
	v_fma_f32 v83, v2, v62, -v83
	ds_write2st64_b32 v105, v62, v63 offset1:1
	s_waitcnt lgkmcnt(0)
	v_add_f32_e32 v83, v60, v83
	v_mul_f32_e32 v60, v2, v63
	v_fmac_f32_e32 v60, v3, v62
	v_add_u32_e32 v63, 32, v105
	v_add_f32_e32 v62, v60, v61
	ds_read2st64_b32 v[60:61], v63 offset0:4 offset1:5
	v_mul_f32_e32 v93, v3, v62
	v_fma_f32 v93, v2, v83, -v93
	ds_write2_b32 v105, v83, v62 offset0:132 offset1:196
	s_waitcnt lgkmcnt(0)
	v_add_f32_e32 v93, v60, v93
	v_mul_f32_e32 v60, v2, v62
	v_fmac_f32_e32 v60, v3, v83
	v_add_f32_e32 v62, v60, v61
	ds_write2st64_b32 v63, v93, v62 offset0:4 offset1:5
	v_add_u32_e32 v63, 48, v105
	ds_read2st64_b32 v[60:61], v63 offset0:6 offset1:7
	v_mul_f32_e32 v83, v3, v62
	v_fma_f32 v83, v2, v93, -v83
	s_waitcnt lgkmcnt(0)
	v_add_f32_e32 v83, v60, v83
	v_mul_f32_e32 v60, v2, v62
	v_fmac_f32_e32 v60, v3, v93
	v_add_f32_e32 v62, v60, v61
	ds_write2st64_b32 v63, v83, v62 offset0:6 offset1:7
	v_add_u32_e32 v63, 64, v105
	ds_read2st64_b32 v[60:61], v63 offset0:8 offset1:9
	v_mul_f32_e32 v93, v3, v62
	v_fma_f32 v93, v2, v83, -v93
	s_waitcnt lgkmcnt(0)
	v_add_f32_e32 v93, v60, v93
	v_mul_f32_e32 v60, v2, v62
	v_fmac_f32_e32 v60, v3, v83
	v_add_f32_e32 v62, v60, v61
	ds_write2st64_b32 v63, v93, v62 offset0:8 offset1:9
	v_add_u32_e32 v63, 0x50, v105
	ds_read2st64_b32 v[60:61], v63 offset0:10 offset1:11
	v_mul_f32_e32 v83, v3, v62
	v_fma_f32 v83, v2, v93, -v83
	s_waitcnt lgkmcnt(0)
	v_add_f32_e32 v83, v60, v83
	v_mul_f32_e32 v60, v2, v62
	v_fmac_f32_e32 v60, v3, v93
	v_add_f32_e32 v62, v60, v61
	ds_write2st64_b32 v63, v83, v62 offset0:10 offset1:11
	v_add_u32_e32 v63, 0x60, v105
	ds_read2st64_b32 v[60:61], v63 offset0:12 offset1:13
	v_mul_f32_e32 v93, v3, v62
	v_fma_f32 v93, v2, v83, -v93
	s_waitcnt lgkmcnt(0)
	v_add_f32_e32 v93, v60, v93
	v_mul_f32_e32 v60, v2, v62
	v_fmac_f32_e32 v60, v3, v83
	v_add_f32_e32 v62, v60, v61
	ds_write2st64_b32 v63, v93, v62 offset0:12 offset1:13
	v_add_u32_e32 v63, 0x70, v105
	ds_read2st64_b32 v[60:61], v63 offset0:14 offset1:15
	v_mul_f32_e32 v83, v3, v62
	v_fma_f32 v83, v2, v93, -v83
	s_waitcnt lgkmcnt(0)
	v_add_f32_e32 v83, v60, v83
	v_mul_f32_e32 v60, v2, v62
	v_fmac_f32_e32 v60, v3, v93
	v_add_f32_e32 v62, v60, v61
	ds_write2st64_b32 v63, v83, v62 offset0:14 offset1:15
	v_add_u32_e32 v63, 0x80, v105
	ds_read2st64_b32 v[60:61], v63 offset0:16 offset1:17
	v_mul_f32_e32 v93, v3, v62
	v_fma_f32 v93, v2, v83, -v93
	s_waitcnt lgkmcnt(0)
	v_add_f32_e32 v93, v60, v93
	v_mul_f32_e32 v60, v2, v62
	v_fmac_f32_e32 v60, v3, v83
	v_add_f32_e32 v62, v60, v61
	ds_write2st64_b32 v63, v93, v62 offset0:16 offset1:17
	v_add_u32_e32 v63, 0x90, v105
	ds_read2st64_b32 v[60:61], v63 offset0:18 offset1:19
	v_mul_f32_e32 v83, v3, v62
	v_fma_f32 v83, v2, v93, -v83
	s_waitcnt lgkmcnt(0)
	v_add_f32_e32 v83, v60, v83
	v_mul_f32_e32 v60, v2, v62
	v_fmac_f32_e32 v60, v3, v93
	v_add_f32_e32 v62, v60, v61
	ds_write2st64_b32 v63, v83, v62 offset0:18 offset1:19
	v_add_u32_e32 v63, 0xa0, v105
	ds_read2st64_b32 v[60:61], v63 offset0:20 offset1:21
	v_mul_f32_e32 v93, v3, v62
	v_fma_f32 v93, v2, v83, -v93
	s_waitcnt lgkmcnt(0)
	v_add_f32_e32 v93, v60, v93
	v_mul_f32_e32 v60, v2, v62
	v_fmac_f32_e32 v60, v3, v83
	v_add_f32_e32 v62, v60, v61
	ds_write2st64_b32 v63, v93, v62 offset0:20 offset1:21
	v_add_u32_e32 v63, 0xb0, v105
	ds_read2st64_b32 v[60:61], v63 offset0:22 offset1:23
	v_mul_f32_e32 v83, v3, v62
	v_fma_f32 v83, v2, v93, -v83
	s_waitcnt lgkmcnt(0)
	v_add_f32_e32 v83, v60, v83
	v_mul_f32_e32 v60, v2, v62
	v_fmac_f32_e32 v60, v3, v93
	v_add_f32_e32 v62, v60, v61
	ds_write2st64_b32 v63, v83, v62 offset0:22 offset1:23
	v_add_u32_e32 v63, 0xc0, v105
	ds_read2st64_b32 v[60:61], v63 offset0:24 offset1:25
	v_mul_f32_e32 v93, v3, v62
	v_fma_f32 v93, v2, v83, -v93
	s_waitcnt lgkmcnt(0)
	v_add_f32_e32 v93, v60, v93
	v_mul_f32_e32 v60, v2, v62
	v_fmac_f32_e32 v60, v3, v83
	v_add_f32_e32 v62, v60, v61
	ds_write2st64_b32 v63, v93, v62 offset0:24 offset1:25
	v_add_u32_e32 v63, 0xd0, v105
	ds_read2st64_b32 v[60:61], v63 offset0:26 offset1:27
	v_mul_f32_e32 v83, v3, v62
	v_fma_f32 v83, v2, v93, -v83
	s_waitcnt lgkmcnt(0)
	v_add_f32_e32 v83, v60, v83
	v_mul_f32_e32 v60, v2, v62
	v_fmac_f32_e32 v60, v3, v93
	v_add_f32_e32 v62, v60, v61
	ds_write2st64_b32 v63, v83, v62 offset0:26 offset1:27
	v_add_u32_e32 v63, 0xe0, v105
	ds_read2st64_b32 v[60:61], v63 offset0:28 offset1:29
	v_mul_f32_e32 v93, v3, v62
	v_mul_f32_e32 v62, v2, v62
	v_fma_f32 v93, v2, v83, -v93
	v_fmac_f32_e32 v62, v3, v83
	v_add_u32_e32 v83, 0xf0, v105
	ds_read2st64_b32 v[96:97], v83 offset0:30 offset1:31
	s_waitcnt lgkmcnt(0)
	v_add_f32_e32 v60, v60, v93
	v_add_f32_e32 v62, v62, v61
	ds_write2st64_b32 v63, v60, v62 offset0:28 offset1:29
	v_pk_mul_f32 v[62:63], v[98:99], v[62:63] op_sel_hi:[1,0]
	s_nop 0
	v_pk_fma_f32 v[114:115], v[2:3], v[60:61], v[62:63] neg_lo:[0,0,1] neg_hi:[0,0,1]
	v_pk_fma_f32 v[60:61], v[2:3], v[60:61], v[62:63] op_sel_hi:[1,0,1]
	s_nop 0
	v_mov_b32_e32 v115, v61
	v_pk_add_f32 v[96:97], v[96:97], v[114:115]
	ds_write2st64_b32 v83, v96, v97 offset0:30 offset1:31
	s_waitcnt lgkmcnt(0)
	ds_read_b128 v[60:63], v100
	ds_read_b128 v[114:117], v100 offset:16
	s_waitcnt lgkmcnt(0)
	v_bfe_u32 v83, v60, 16, 1
	v_add3_u32 v60, v60, v83, s23
	v_bfe_u32 v83, v61, 16, 1
	v_lshrrev_b32_e32 v60, 16, v60
	v_add3_u32 v61, v61, v83, s23
	v_and_or_b32 v60, v61, s15, v60
	v_and_b32_sdwa v61, v63, v225 dst_sel:DWORD dst_unused:UNUSED_PAD src0_sel:WORD_1 src1_sel:DWORD
	v_and_b32_sdwa v83, v62, v225 dst_sel:DWORD dst_unused:UNUSED_PAD src0_sel:WORD_1 src1_sel:DWORD
	v_add3_u32 v62, v62, v83, s23
	v_add3_u32 v61, v63, v61, s23
	v_perm_b32 v61, v61, v62, s22
	v_and_b32_sdwa v62, v115, v225 dst_sel:DWORD dst_unused:UNUSED_PAD src0_sel:WORD_1 src1_sel:DWORD
	v_and_b32_sdwa v63, v114, v225 dst_sel:DWORD dst_unused:UNUSED_PAD src0_sel:WORD_1 src1_sel:DWORD
	v_add3_u32 v63, v114, v63, s23
	v_add3_u32 v62, v115, v62, s23
	v_perm_b32 v62, v62, v63, s22
	v_and_b32_sdwa v63, v117, v225 dst_sel:DWORD dst_unused:UNUSED_PAD src0_sel:WORD_1 src1_sel:DWORD
	v_and_b32_sdwa v83, v116, v225 dst_sel:DWORD dst_unused:UNUSED_PAD src0_sel:WORD_1 src1_sel:DWORD
	v_add3_u32 v83, v116, v83, s23
	v_add3_u32 v63, v117, v63, s23
	ds_read_b128 v[114:117], v100 offset:128
	ds_read_b128 v[118:121], v100 offset:144
	v_perm_b32 v63, v63, v83, s22
	s_waitcnt lgkmcnt(0)
	v_bfe_u32 v83, v114, 16, 1
	v_add3_u32 v83, v114, v83, s23
	v_bfe_u32 v93, v115, 16, 1
	v_lshrrev_b32_e32 v83, 16, v83
	v_add3_u32 v93, v115, v93, s23
	v_and_or_b32 v114, v93, s15, v83
	v_and_b32_sdwa v83, v117, v225 dst_sel:DWORD dst_unused:UNUSED_PAD src0_sel:WORD_1 src1_sel:DWORD
	v_and_b32_sdwa v93, v116, v225 dst_sel:DWORD dst_unused:UNUSED_PAD src0_sel:WORD_1 src1_sel:DWORD
	v_add3_u32 v93, v116, v93, s23
	v_add3_u32 v83, v117, v83, s23
	v_perm_b32 v115, v83, v93, s22
	v_and_b32_sdwa v83, v119, v225 dst_sel:DWORD dst_unused:UNUSED_PAD src0_sel:WORD_1 src1_sel:DWORD
	v_and_b32_sdwa v93, v118, v225 dst_sel:DWORD dst_unused:UNUSED_PAD src0_sel:WORD_1 src1_sel:DWORD
	v_mfma_f32_16x16x32_bf16 v[60:63], v[40:43], v[60:63], 0
	v_add3_u32 v93, v118, v93, s23
	v_add3_u32 v83, v119, v83, s23
	v_perm_b32 v116, v83, v93, s22
	v_and_b32_sdwa v83, v121, v225 dst_sel:DWORD dst_unused:UNUSED_PAD src0_sel:WORD_1 src1_sel:DWORD
	v_and_b32_sdwa v93, v120, v225 dst_sel:DWORD dst_unused:UNUSED_PAD src0_sel:WORD_1 src1_sel:DWORD
	v_add3_u32 v93, v120, v93, s23
	v_add3_u32 v83, v121, v83, s23
	v_perm_b32 v117, v83, v93, s22
	s_nop 1
	v_mfma_f32_16x16x32_bf16 v[60:63], v[44:47], v[114:117], v[60:63]
	ds_read_b128 v[114:117], v100 offset:256
	ds_read_b128 v[118:121], v100 offset:272
	s_waitcnt lgkmcnt(0)
	v_bfe_u32 v83, v114, 16, 1
	v_add3_u32 v83, v114, v83, s23
	v_bfe_u32 v93, v115, 16, 1
	v_lshrrev_b32_e32 v83, 16, v83
	v_add3_u32 v93, v115, v93, s23
	v_and_or_b32 v114, v93, s15, v83
	v_and_b32_sdwa v83, v117, v225 dst_sel:DWORD dst_unused:UNUSED_PAD src0_sel:WORD_1 src1_sel:DWORD
	v_and_b32_sdwa v93, v116, v225 dst_sel:DWORD dst_unused:UNUSED_PAD src0_sel:WORD_1 src1_sel:DWORD
	v_add3_u32 v93, v116, v93, s23
	v_add3_u32 v83, v117, v83, s23
	v_perm_b32 v115, v83, v93, s22
	v_and_b32_sdwa v83, v119, v225 dst_sel:DWORD dst_unused:UNUSED_PAD src0_sel:WORD_1 src1_sel:DWORD
	v_and_b32_sdwa v93, v118, v225 dst_sel:DWORD dst_unused:UNUSED_PAD src0_sel:WORD_1 src1_sel:DWORD
	v_add3_u32 v93, v118, v93, s23
	v_add3_u32 v83, v119, v83, s23
	v_perm_b32 v116, v83, v93, s22
	v_and_b32_sdwa v83, v121, v225 dst_sel:DWORD dst_unused:UNUSED_PAD src0_sel:WORD_1 src1_sel:DWORD
	v_and_b32_sdwa v93, v120, v225 dst_sel:DWORD dst_unused:UNUSED_PAD src0_sel:WORD_1 src1_sel:DWORD
	v_add3_u32 v93, v120, v93, s23
	v_add3_u32 v83, v121, v83, s23
	v_perm_b32 v117, v83, v93, s22
	s_nop 1
	v_mfma_f32_16x16x32_bf16 v[60:63], v[48:51], v[114:117], v[60:63]
	ds_read_b128 v[114:117], v100 offset:384
	ds_read_b128 v[118:121], v100 offset:400
	s_waitcnt lgkmcnt(0)
	s_waitcnt lgkmcnt(0)
	v_bfe_u32 v83, v114, 16, 1
	v_add3_u32 v83, v114, v83, s23
	v_bfe_u32 v93, v115, 16, 1
	v_lshrrev_b32_e32 v83, 16, v83
	v_add3_u32 v93, v115, v93, s23
	v_and_or_b32 v114, v93, s15, v83
	v_and_b32_sdwa v83, v117, v225 dst_sel:DWORD dst_unused:UNUSED_PAD src0_sel:WORD_1 src1_sel:DWORD
	v_and_b32_sdwa v93, v116, v225 dst_sel:DWORD dst_unused:UNUSED_PAD src0_sel:WORD_1 src1_sel:DWORD
	v_add3_u32 v93, v116, v93, s23
	v_add3_u32 v83, v117, v83, s23
	v_perm_b32 v115, v83, v93, s22
	v_and_b32_sdwa v83, v119, v225 dst_sel:DWORD dst_unused:UNUSED_PAD src0_sel:WORD_1 src1_sel:DWORD
	v_and_b32_sdwa v93, v118, v225 dst_sel:DWORD dst_unused:UNUSED_PAD src0_sel:WORD_1 src1_sel:DWORD
	v_add3_u32 v93, v118, v93, s23
	v_add3_u32 v83, v119, v83, s23
	v_perm_b32 v116, v83, v93, s22
	v_and_b32_sdwa v83, v121, v225 dst_sel:DWORD dst_unused:UNUSED_PAD src0_sel:WORD_1 src1_sel:DWORD
	v_and_b32_sdwa v93, v120, v225 dst_sel:DWORD dst_unused:UNUSED_PAD src0_sel:WORD_1 src1_sel:DWORD
	v_add3_u32 v93, v120, v93, s23
	v_add3_u32 v83, v121, v83, s23
	v_perm_b32 v117, v83, v93, s22
	s_nop 1
	v_mfma_f32_16x16x32_bf16 v[60:63], v[52:55], v[114:117], v[60:63]
	s_waitcnt vmcnt(0)
	s_nop 6
	v_pk_fma_f32 v[56:57], v[4:5], v[56:57], v[60:61]
	v_pk_fma_f32 v[58:59], v[6:7], v[58:59], v[62:63]
	v_mul_f32_e32 v62, 0x3d372713, v56
	v_mul_f32_e32 v83, 0x3d372713, v57
	v_mul_f32_e32 v62, v56, v62
	v_mul_f32_e32 v83, v57, v83
	v_mov_b32_e32 v60, v56
	v_fma_f32 v56, v56, v62, v56
	v_mov_b32_e32 v62, v57
	v_fmac_f32_e32 v57, v57, v83
	v_mul_f32_e32 v57, 0x3f4c422a, v57
	v_add_f32_e32 v57, v57, v57
	v_mul_f32_e32 v57, 0x3fb8aa3b, v57
	v_exp_f32_e32 v114, v57
	v_mul_f32_e32 v57, 0x3d372713, v58
	v_mul_f32_e32 v57, v58, v57
	v_fma_f32 v57, v58, v57, v58
	v_mul_f32_e32 v56, 0x3f4c422a, v56
	v_mul_f32_e32 v57, 0x3f4c422a, v57
	v_add_f32_e32 v56, v56, v56
	v_add_f32_e32 v57, v57, v57
	v_mul_f32_e32 v56, 0x3fb8aa3b, v56
	v_mul_f32_e32 v57, 0x3fb8aa3b, v57
	v_exp_f32_e32 v56, v56
	v_exp_f32_e32 v57, v57
	v_mov_b32_e32 v61, v58
	v_mov_b32_e32 v63, v59
	v_pk_mul_f32 v[60:61], v[60:61], 0.5 op_sel_hi:[1,0]
	v_pk_add_f32 v[56:57], v[56:57], 1.0 op_sel_hi:[1,0]
	s_nop 0
	s_nop 0
	v_rcp_f32_e32 v57, v57
	s_nop 0
	s_nop 0
	v_rcp_f32_e32 v56, v56
	s_nop 0
	v_mul_f32_e32 v58, 0x3d372713, v59
	v_mul_f32_e32 v58, v59, v58
	v_fmac_f32_e32 v59, v59, v58
	v_mul_f32_e32 v58, 0x3f4c422a, v59
	v_add_f32_e32 v58, v58, v58
	v_mul_f32_e32 v58, 0x3fb8aa3b, v58
	v_exp_f32_e32 v115, v58
	v_pk_fma_f32 v[56:57], v[56:57], 2.0, 1.0 op_sel_hi:[1,0,0] neg_lo:[1,0,0] neg_hi:[1,0,0]
	v_pk_add_f32 v[58:59], v[114:115], 1.0 op_sel_hi:[1,0]
	v_pk_add_f32 v[56:57], v[56:57], 1.0 op_sel_hi:[1,0]
	s_nop 0
	v_pk_mul_f32 v[56:57], v[60:61], v[56:57]
	s_nop 0
	v_rcp_f32_e32 v59, v59
	s_nop 0
	s_nop 0
	v_rcp_f32_e32 v58, v58
	s_nop 0
	v_pk_fma_f32 v[58:59], v[58:59], 2.0, 1.0 op_sel_hi:[1,0,0] neg_lo:[1,0,0] neg_hi:[1,0,0]
	v_pk_mul_f32 v[60:61], v[62:63], 0.5 op_sel_hi:[1,0]
	v_pk_add_f32 v[58:59], v[58:59], 1.0 op_sel_hi:[1,0]
	s_andn2_b64 vcc, exec, s[6:7]
	v_pk_mul_f32 v[58:59], v[60:61], v[58:59]
	v_and_b32_sdwa v61, v56, v225 dst_sel:DWORD dst_unused:UNUSED_PAD src0_sel:WORD_1 src1_sel:DWORD
	v_and_b32_sdwa v60, v57, v225 dst_sel:DWORD dst_unused:UNUSED_PAD src0_sel:WORD_1 src1_sel:DWORD
	v_add3_u32 v56, v56, v61, s23
	v_and_b32_sdwa v61, v58, v225 dst_sel:DWORD dst_unused:UNUSED_PAD src0_sel:WORD_1 src1_sel:DWORD
	v_add3_u32 v57, v57, v60, s23
	v_and_b32_sdwa v60, v59, v225 dst_sel:DWORD dst_unused:UNUSED_PAD src0_sel:WORD_1 src1_sel:DWORD
	v_add3_u32 v58, v58, v61, s23
	v_add3_u32 v59, v59, v60, s23
	v_and_b32_e32 v58, 0xffff0000, v58
	v_and_b32_e32 v59, 0xffff0000, v59
	v_or_b32_sdwa v56, v58, v56 dst_sel:DWORD dst_unused:UNUSED_PAD src0_sel:DWORD src1_sel:WORD_1
	v_or_b32_e32 v58, s18, v64
	v_or_b32_sdwa v57, v59, v57 dst_sel:DWORD dst_unused:UNUSED_PAD src0_sel:DWORD src1_sel:WORD_1
	v_mad_u32_u24 v58, v58, s17, v81
	s_mov_b32 s18, 16
	ds_write_b64 v58, v[56:57]
	s_cbranch_vccz .LBB0_1196
	v_mov_b32_e32 v132, v144
	v_mov_b32_e32 v133, v145
	v_mov_b32_e32 v134, v146
	v_mov_b32_e32 v135, v147
	v_mov_b32_e32 v136, v148
	v_mov_b32_e32 v137, v149
	v_mov_b32_e32 v138, v150
	v_mov_b32_e32 v139, v151
	v_mov_b32_e32 v140, v152
	v_mov_b32_e32 v141, v153
	v_mov_b32_e32 v142, v154
	v_mov_b32_e32 v143, v155
.LBB0_1199:
	v_or_b32_e32 v58, s18, v92
	v_mov_b64_e32 v[56:57], s[0:1]
	v_mad_i64_i32 v[56:57], s[6:7], v58, s20, v[56:57]
	v_lshl_add_u64 v[56:57], s[4:5], 2, v[56:57]
	v_lshl_add_u64 v[56:57], v[56:57], 0, s[94:95]
	v_mov_b32_e32 v60, 0
	v_mov_b32_e32 v61, 0
	v_mov_b32_e32 v62, 0
	v_mov_b32_e32 v63, 0
	s_and_saveexec_b64 s[6:7], s[42:43]
	s_cbranch_execz .LBB0_1198
	v_mov_b32_e32 v83, v1
	v_lshl_add_u64 v[62:63], v[56:57], 0, v[82:83]
	v_mov_b32_e32 v58, v132
	v_mov_b32_e32 v59, v133
	v_mov_b32_e32 v60, v134
	v_mov_b32_e32 v61, v135
	v_mov_b32_e32 v114, v136
	v_mov_b32_e32 v115, v137
	v_mov_b32_e32 v116, v138
	v_mov_b32_e32 v117, v139
	s_waitcnt vmcnt(0) lgkmcnt(0)
	v_bfe_u32 v62, v58, 16, 1
	v_bfe_u32 v63, v59, 16, 1
	v_and_b32_sdwa v83, v61, v225 dst_sel:DWORD dst_unused:UNUSED_PAD src0_sel:WORD_1 src1_sel:DWORD
	v_and_b32_sdwa v93, v60, v225 dst_sel:DWORD dst_unused:UNUSED_PAD src0_sel:WORD_1 src1_sel:DWORD
	v_and_b32_sdwa v118, v115, v225 dst_sel:DWORD dst_unused:UNUSED_PAD src0_sel:WORD_1 src1_sel:DWORD
	v_and_b32_sdwa v119, v114, v225 dst_sel:DWORD dst_unused:UNUSED_PAD src0_sel:WORD_1 src1_sel:DWORD
	v_and_b32_sdwa v120, v117, v225 dst_sel:DWORD dst_unused:UNUSED_PAD src0_sel:WORD_1 src1_sel:DWORD
	v_and_b32_sdwa v121, v116, v225 dst_sel:DWORD dst_unused:UNUSED_PAD src0_sel:WORD_1 src1_sel:DWORD
	v_add3_u32 v58, v58, v62, s23
	v_add3_u32 v59, v59, v63, s23
	v_add3_u32 v60, v60, v93, s23
	v_add3_u32 v61, v61, v83, s23
	v_add3_u32 v62, v114, v119, s23
	v_add3_u32 v63, v115, v118, s23
	v_add3_u32 v83, v116, v121, s23
	v_add3_u32 v93, v117, v120, s23
	v_lshrrev_b32_e32 v58, 16, v58
	v_perm_b32 v61, v61, v60, s22
	v_perm_b32 v62, v63, v62, s22
	v_and_or_b32 v60, v59, s15, v58
	v_perm_b32 v63, v93, v83, s22
	s_branch .LBB0_1198

	.amdhsa_kernel _Z10hybrid_fwd4Args
		.amdhsa_group_segment_fixed_size 0
		.amdhsa_private_segment_fixed_size 0
		.amdhsa_kernarg_size 472
		.amdhsa_user_sgpr_count 2
		.amdhsa_user_sgpr_dispatch_ptr 0
		.amdhsa_user_sgpr_queue_ptr 0
		.amdhsa_user_sgpr_kernarg_segment_ptr 1
		.amdhsa_user_sgpr_dispatch_id 0
		.amdhsa_user_sgpr_kernarg_preload_length 0
		.amdhsa_user_sgpr_kernarg_preload_offset 0
		.amdhsa_user_sgpr_private_segment_size 0
		.amdhsa_uses_dynamic_stack 0
		.amdhsa_enable_private_segment 0
		.amdhsa_system_sgpr_workgroup_id_x 1
		.amdhsa_system_sgpr_workgroup_id_y 0
		.amdhsa_system_sgpr_workgroup_id_z 0
		.amdhsa_system_sgpr_workgroup_info 0
		.amdhsa_system_vgpr_workitem_id 2
		.amdhsa_next_free_vgpr 256
		.amdhsa_next_free_sgpr 102
		.amdhsa_accum_offset 256
		.amdhsa_reserve_vcc 1
		.amdhsa_float_round_mode_32 0
		.amdhsa_float_round_mode_16_64 0
		.amdhsa_float_denorm_mode_32 3
		.amdhsa_float_denorm_mode_16_64 3
		.amdhsa_dx10_clamp 1
		.amdhsa_ieee_mode 1
		.amdhsa_fp16_overflow 0
		.amdhsa_tg_split 0
		.amdhsa_exception_fp_ieee_invalid_op 0
		.amdhsa_exception_fp_denorm_src 0
		.amdhsa_exception_fp_ieee_div_zero 0
		.amdhsa_exception_fp_ieee_overflow 0
		.amdhsa_exception_fp_ieee_underflow 0
		.amdhsa_exception_fp_ieee_inexact 0
		.amdhsa_exception_int_div_zero 0
	.end_amdhsa_kernel

amdhsa.kernels:
  - .agpr_count:     0
    .args:
      - .offset:         0
        .size:           216
        .value_kind:     by_value
      - .offset:         216
        .size:           4
        .value_kind:     hidden_block_count_x
      - .offset:         220
        .size:           4
        .value_kind:     hidden_block_count_y
      - .offset:         224
        .size:           4
        .value_kind:     hidden_block_count_z
      - .offset:         228
        .size:           2
        .value_kind:     hidden_group_size_x
      - .offset:         230
        .size:           2
        .value_kind:     hidden_group_size_y
      - .offset:         232
        .size:           2
        .value_kind:     hidden_group_size_z
      - .offset:         234
        .size:           2
        .value_kind:     hidden_remainder_x
      - .offset:         236
        .size:           2
        .value_kind:     hidden_remainder_y
      - .offset:         238
        .size:           2
        .value_kind:     hidden_remainder_z
      - .offset:         256
        .size:           8
        .value_kind:     hidden_global_offset_x
      - .offset:         264
        .size:           8
        .value_kind:     hidden_global_offset_y
      - .offset:         272
        .size:           8
        .value_kind:     hidden_global_offset_z
      - .offset:         280
        .size:           2
        .value_kind:     hidden_grid_dims
      - .offset:         304
        .size:           8
        .value_kind:     hidden_multigrid_sync_arg
      - .offset:         336
        .size:           4
        .value_kind:     hidden_dynamic_lds_size
    .group_segment_fixed_size: 0
    .kernarg_segment_align: 8
    .kernarg_segment_size: 472
    .language:       OpenCL C
    .language_version:
      - 2
      - 0
    .max_flat_workgroup_size: 512
    .name:           _Z10hybrid_fwd4Args
    .private_segment_fixed_size: 0
    .sgpr_count:     108
    .sgpr_spill_count: 221
    .symbol:         _Z10hybrid_fwd4Args.kd
    .uniform_work_group_size: 1
    .uses_dynamic_stack: false
    .vgpr_count:     256
    .vgpr_spill_count: 0
    .wavefront_size: 64
